# scan waves at s_setprio 3
# speedup vs baseline: 1.0028x; 1.0028x over previous
.LBB0_496:
	s_setprio 0
	s_add_i32 s76, s76, 1
	s_mov_b64 s[0:1], 0

.LBB0_501:
	s_setprio 3
	s_mov_b64 s[0:1], s[30:31]
	v_mov_b32_e32 v0, v117
	s_bfe_u32 s78, s77, 0x10001
	s_add_u32 s24, s0, 0x156d7900
	v_mbcnt_lo_u32_b32 v0, -1, v0
	v_mbcnt_hi_u32_b32 v0, -1, v0
	s_addc_u32 s25, s1, 0
	v_add_u32_e32 v38, s33, v0
	s_add_u32 s6, s0, 0x168d7900
	s_addc_u32 s7, s1, 0
	s_mul_i32 s4, s78, 0x1200000
	v_mul_hi_i32 v0, v38, s19
	s_add_u32 s4, s0, s4
	v_lshrrev_b32_e32 v1, 31, v0
	v_ashrrev_i32_e32 v0, 4, v0
	s_addc_u32 s5, s1, 0
	v_add_u32_e32 v39, v0, v1
	s_add_u32 s8, s4, 0x18cd7900
	v_mad_u64_u32 v[0:1], s[26:27], v39, s21, v[38:39]
	s_addc_u32 s9, s5, 0
	v_ashrrev_i32_e32 v40, 3, v0
	v_cmp_lt_u32_e32 vcc, 7, v0
	v_mov_b64_e32 v[0:1], s[24:25]
	s_and_saveexec_b64 s[26:27], vcc
	s_cbranch_execz .LBB0_509
	v_cmp_lt_i32_e32 vcc, 1, v40
	s_mov_b64 s[34:35], 0
	s_and_saveexec_b64 s[50:51], vcc
	s_xor_b64 s[50:51], exec, s[50:51]
	s_cbranch_execz .LBB0_569
	v_cmp_eq_u32_e32 vcc, 2, v40
	s_mov_b64 s[34:35], -1
	s_and_saveexec_b64 s[52:53], vcc
	s_xor_b64 s[34:35], exec, -1
	s_or_b64 exec, exec, s[52:53]
	s_and_b64 s[34:35], s[34:35], exec
	s_or_saveexec_b64 s[50:51], s[50:51]
	v_mov_b64_e32 v[0:1], s[8:9]
	s_xor_b64 exec, exec, s[50:51]
	s_cbranch_execnz .LBB0_570

.LBB0_1479:
	s_setprio 0
	s_add_i32 s78, s78, 1
	s_mov_b64 s[0:1], 0

.LBB0_1484:
	s_setprio 3
	s_mov_b64 s[0:1], s[30:31]
	v_mov_b32_e32 v0, v117
	s_bfe_u32 s80, s79, 0x10001
	s_add_u32 s24, s0, 0x156d7900
	v_mbcnt_lo_u32_b32 v0, -1, v0
	v_mbcnt_hi_u32_b32 v0, -1, v0
	s_addc_u32 s25, s1, 0
	v_add_u32_e32 v38, s33, v0
	s_add_u32 s6, s0, 0x168d7900
	s_addc_u32 s7, s1, 0
	s_mul_i32 s4, s80, 0x1200000
	v_mul_hi_i32 v0, v38, s21
	s_add_u32 s4, s0, s4
	v_lshrrev_b32_e32 v1, 31, v0
	v_ashrrev_i32_e32 v0, 4, v0
	s_addc_u32 s5, s1, 0
	v_add_u32_e32 v39, v0, v1
	s_add_u32 s8, s4, 0x18cd7900
	v_mad_u64_u32 v[0:1], s[26:27], v39, s23, v[38:39]
	s_addc_u32 s9, s5, 0
	v_ashrrev_i32_e32 v40, 3, v0
	v_cmp_lt_u32_e32 vcc, 7, v0
	v_mov_b64_e32 v[0:1], s[24:25]
	s_and_saveexec_b64 s[26:27], vcc
	s_cbranch_execz .LBB0_1492
	v_cmp_lt_i32_e32 vcc, 1, v40
	s_mov_b64 s[34:35], 0
	s_and_saveexec_b64 s[52:53], vcc
	s_xor_b64 s[52:53], exec, s[52:53]
	s_cbranch_execz .LBB0_1552
	v_cmp_eq_u32_e32 vcc, 2, v40
	s_mov_b64 s[34:35], -1
	s_and_saveexec_b64 s[54:55], vcc
	s_xor_b64 s[34:35], exec, -1
	s_or_b64 exec, exec, s[54:55]
	s_and_b64 s[34:35], s[34:35], exec
	s_or_saveexec_b64 s[52:53], s[52:53]
	v_mov_b64_e32 v[0:1], s[8:9]
	s_xor_b64 exec, exec, s[52:53]
	s_cbranch_execnz .LBB0_1553
